# P8 deferred latent-row fix-up hand-written for the 256-WG grid: all six rounds of hbp/hbh/conv_w loads issued before the first wait (was one dependent round trip per round)
# baseline (speedup 1.0000x reference)
.LBB0_1577:
	s_cmp_lt_i32 s78, 9
	s_cselect_b64 s[2:3], -1, 0
	s_and_b64 s[10:11], s[2:3], s[0:1]
	s_andn2_b64 vcc, exec, s[10:11]
	s_cbranch_vccnz .LBB0_1673
	s_add_u32 s82, s76, 0x9e00000
	s_addc_u32 s83, s77, 0
	s_cmpk_lg_i32 s92, 0x100
	s_cselect_b64 s[2:3], -1, 0
	s_and_b32 s30, s96, 3
	s_lshl_b32 s4, s96, 9
	s_cmpk_eq_i32 s92, 0x100
	s_waitcnt lgkmcnt(0)
	s_cselect_b64 s[70:71], -1, 0
	s_and_b64 s[0:1], s[70:71], exec
	s_movk_i32 s5, 0xb00
	s_cselect_b32 s0, 0, s4
	s_cselect_b32 s20, s5, 0x16000
	s_and_b64 vcc, exec, s[70:71]
	s_cbranch_vccz .Lfx_generic
	s_add_u32 s6, s76, 0x18b00000
	s_addc_u32 s7, s77, 0
	s_add_u32 s8, s76, 0x18c00000
	s_addc_u32 s9, s77, 0
	v_readlane_b32 s42, v253, 12
	v_readlane_b32 s43, v253, 13
	s_lshr_b32 s0, s96, 2
	s_and_b32 s0, s0, 7
	s_and_b32 s1, s0, 3
	s_cmp_eq_u32 s1, 0
	s_cselect_b64 s[54:55], -1, 0
	s_cmp_eq_u32 s1, 3
	s_cselect_b64 s[56:57], -1, 0
	s_mul_i32 s12, s30, 0x580
	s_lshl_b32 s13, s0, 1
	s_mul_i32 s14, s13, 0xb000
	s_sub_u32 s15, s14, 0xb000
	s_lshl_b32 s18, s0, 8
	s_add_u32 s18, s18, 0x2000
	s_mul_i32 s18, s18, 0x2c00
	s_mov_b32 s20, 0xb000
	s_mov_b32 s22, 0x21000
	s_mov_b32 s23, 0x16000
	s_mov_b32 s26, 0x2bd400
	s_movk_i32 s28, 0xb00
	v_mov_b32_e32 v2, v243
	v_cmp_lt_u32_e32 vcc, 0x57f, v2
	s_nop 1
	v_cndmask_b32_e64 v3, 0, 1, vcc
	v_mul_u32_u24_e32 v4, 0x580, v3
	v_sub_u32_e32 v4, v2, v4
	v_add_u32_e32 v4, s12, v4
	v_lshlrev_b32_e32 v5, 2, v4
	v_mad_u32_u24 v6, v3, s20, v5
	v_add_u32_e32 v6, s14, v6
	v_mad_u32_u24 v7, v3, s22, v5
	v_add_u32_e32 v7, s15, v7
	v_mad_u32_u24 v8, v3, s23, v5
	v_lshlrev_b32_e32 v9, 1, v4
	v_mad_u32_u24 v9, v3, s26, v9
	v_add_u32_e32 v100, s18, v9
	v_cmp_gt_u32_e64 s[58:59], s28, v2
	s_and_b64 s[44:45], vcc, s[56:57]
	s_andn2_b64 s[46:47], s[54:55], vcc
	s_or_b64 s[44:45], s[44:45], s[46:47]
	s_andn2_b64 s[58:59], s[58:59], s[44:45]
	s_mov_b64 exec, s[58:59]
	global_load_dword v60, v6, s[6:7]
	global_load_dword v61, v7, s[8:9]
	global_load_dword v62, v8, s[42:43]
	v_add_u32_e32 v6, 0x5800, v6
	v_add_u32_e32 v7, 0x5800, v7
	v_add_u32_e32 v8, 0x5800, v8
	global_load_dword v63, v6, s[6:7]
	global_load_dword v64, v7, s[8:9]
	global_load_dword v65, v8, s[42:43]
	s_mov_b64 exec, -1
	v_add_u32_e32 v2, 512, v243
	v_cmp_lt_u32_e32 vcc, 0x57f, v2
	s_nop 1
	v_cndmask_b32_e64 v3, 0, 1, vcc
	v_mul_u32_u24_e32 v4, 0x580, v3
	v_sub_u32_e32 v4, v2, v4
	v_add_u32_e32 v4, s12, v4
	v_lshlrev_b32_e32 v5, 2, v4
	v_mad_u32_u24 v6, v3, s20, v5
	v_add_u32_e32 v6, s14, v6
	v_mad_u32_u24 v7, v3, s22, v5
	v_add_u32_e32 v7, s15, v7
	v_mad_u32_u24 v8, v3, s23, v5
	v_lshlrev_b32_e32 v9, 1, v4
	v_mad_u32_u24 v9, v3, s26, v9
	v_add_u32_e32 v101, s18, v9
	v_cmp_gt_u32_e64 s[60:61], s28, v2
	s_and_b64 s[44:45], vcc, s[56:57]
	s_andn2_b64 s[46:47], s[54:55], vcc
	s_or_b64 s[44:45], s[44:45], s[46:47]
	s_andn2_b64 s[60:61], s[60:61], s[44:45]
	s_mov_b64 exec, s[60:61]
	global_load_dword v66, v6, s[6:7]
	global_load_dword v67, v7, s[8:9]
	global_load_dword v68, v8, s[42:43]
	v_add_u32_e32 v6, 0x5800, v6
	v_add_u32_e32 v7, 0x5800, v7
	v_add_u32_e32 v8, 0x5800, v8
	global_load_dword v69, v6, s[6:7]
	global_load_dword v70, v7, s[8:9]
	global_load_dword v71, v8, s[42:43]
	s_mov_b64 exec, -1
	v_add_u32_e32 v2, 1024, v243
	v_cmp_lt_u32_e32 vcc, 0x57f, v2
	s_nop 1
	v_cndmask_b32_e64 v3, 0, 1, vcc
	v_mul_u32_u24_e32 v4, 0x580, v3
	v_sub_u32_e32 v4, v2, v4
	v_add_u32_e32 v4, s12, v4
	v_lshlrev_b32_e32 v5, 2, v4
	v_mad_u32_u24 v6, v3, s20, v5
	v_add_u32_e32 v6, s14, v6
	v_mad_u32_u24 v7, v3, s22, v5
	v_add_u32_e32 v7, s15, v7
	v_mad_u32_u24 v8, v3, s23, v5
	v_lshlrev_b32_e32 v9, 1, v4
	v_mad_u32_u24 v9, v3, s26, v9
	v_add_u32_e32 v102, s18, v9
	v_cmp_gt_u32_e64 s[62:63], s28, v2
	s_and_b64 s[44:45], vcc, s[56:57]
	s_andn2_b64 s[46:47], s[54:55], vcc
	s_or_b64 s[44:45], s[44:45], s[46:47]
	s_andn2_b64 s[62:63], s[62:63], s[44:45]
	s_mov_b64 exec, s[62:63]
	global_load_dword v72, v6, s[6:7]
	global_load_dword v73, v7, s[8:9]
	global_load_dword v74, v8, s[42:43]
	v_add_u32_e32 v6, 0x5800, v6
	v_add_u32_e32 v7, 0x5800, v7
	v_add_u32_e32 v8, 0x5800, v8
	global_load_dword v75, v6, s[6:7]
	global_load_dword v76, v7, s[8:9]
	global_load_dword v77, v8, s[42:43]
	s_mov_b64 exec, -1
	v_add_u32_e32 v2, 1536, v243
	v_cmp_lt_u32_e32 vcc, 0x57f, v2
	s_nop 1
	v_cndmask_b32_e64 v3, 0, 1, vcc
	v_mul_u32_u24_e32 v4, 0x580, v3
	v_sub_u32_e32 v4, v2, v4
	v_add_u32_e32 v4, s12, v4
	v_lshlrev_b32_e32 v5, 2, v4
	v_mad_u32_u24 v6, v3, s20, v5
	v_add_u32_e32 v6, s14, v6
	v_mad_u32_u24 v7, v3, s22, v5
	v_add_u32_e32 v7, s15, v7
	v_mad_u32_u24 v8, v3, s23, v5
	v_lshlrev_b32_e32 v9, 1, v4
	v_mad_u32_u24 v9, v3, s26, v9
	v_add_u32_e32 v103, s18, v9
	v_cmp_gt_u32_e64 s[64:65], s28, v2
	s_and_b64 s[44:45], vcc, s[56:57]
	s_andn2_b64 s[46:47], s[54:55], vcc
	s_or_b64 s[44:45], s[44:45], s[46:47]
	s_andn2_b64 s[64:65], s[64:65], s[44:45]
	s_mov_b64 exec, s[64:65]
	global_load_dword v78, v6, s[6:7]
	global_load_dword v79, v7, s[8:9]
	global_load_dword v80, v8, s[42:43]
	v_add_u32_e32 v6, 0x5800, v6
	v_add_u32_e32 v7, 0x5800, v7
	v_add_u32_e32 v8, 0x5800, v8
	global_load_dword v81, v6, s[6:7]
	global_load_dword v82, v7, s[8:9]
	global_load_dword v83, v8, s[42:43]
	s_mov_b64 exec, -1
	v_add_u32_e32 v2, 2048, v243
	v_cmp_lt_u32_e32 vcc, 0x57f, v2
	s_nop 1
	v_cndmask_b32_e64 v3, 0, 1, vcc
	v_mul_u32_u24_e32 v4, 0x580, v3
	v_sub_u32_e32 v4, v2, v4
	v_add_u32_e32 v4, s12, v4
	v_lshlrev_b32_e32 v5, 2, v4
	v_mad_u32_u24 v6, v3, s20, v5
	v_add_u32_e32 v6, s14, v6
	v_mad_u32_u24 v7, v3, s22, v5
	v_add_u32_e32 v7, s15, v7
	v_mad_u32_u24 v8, v3, s23, v5
	v_lshlrev_b32_e32 v9, 1, v4
	v_mad_u32_u24 v9, v3, s26, v9
	v_add_u32_e32 v104, s18, v9
	v_cmp_gt_u32_e64 s[66:67], s28, v2
	s_and_b64 s[44:45], vcc, s[56:57]
	s_andn2_b64 s[46:47], s[54:55], vcc
	s_or_b64 s[44:45], s[44:45], s[46:47]
	s_andn2_b64 s[66:67], s[66:67], s[44:45]
	s_mov_b64 exec, s[66:67]
	global_load_dword v84, v6, s[6:7]
	global_load_dword v85, v7, s[8:9]
	global_load_dword v86, v8, s[42:43]
	v_add_u32_e32 v6, 0x5800, v6
	v_add_u32_e32 v7, 0x5800, v7
	v_add_u32_e32 v8, 0x5800, v8
	global_load_dword v87, v6, s[6:7]
	global_load_dword v88, v7, s[8:9]
	global_load_dword v89, v8, s[42:43]
	s_mov_b64 exec, -1
	v_add_u32_e32 v2, 2560, v243
	v_cmp_lt_u32_e32 vcc, 0x57f, v2
	s_nop 1
	v_cndmask_b32_e64 v3, 0, 1, vcc
	v_mul_u32_u24_e32 v4, 0x580, v3
	v_sub_u32_e32 v4, v2, v4
	v_add_u32_e32 v4, s12, v4
	v_lshlrev_b32_e32 v5, 2, v4
	v_mad_u32_u24 v6, v3, s20, v5
	v_add_u32_e32 v6, s14, v6
	v_mad_u32_u24 v7, v3, s22, v5
	v_add_u32_e32 v7, s15, v7
	v_mad_u32_u24 v8, v3, s23, v5
	v_lshlrev_b32_e32 v9, 1, v4
	v_mad_u32_u24 v9, v3, s26, v9
	v_add_u32_e32 v105, s18, v9
	v_cmp_gt_u32_e64 s[68:69], s28, v2
	s_and_b64 s[44:45], vcc, s[56:57]
	s_andn2_b64 s[46:47], s[54:55], vcc
	s_or_b64 s[44:45], s[44:45], s[46:47]
	s_andn2_b64 s[68:69], s[68:69], s[44:45]
	s_mov_b64 exec, s[68:69]
	global_load_dword v90, v6, s[6:7]
	global_load_dword v91, v7, s[8:9]
	global_load_dword v92, v8, s[42:43]
	v_add_u32_e32 v6, 0x5800, v6
	v_add_u32_e32 v7, 0x5800, v7
	v_add_u32_e32 v8, 0x5800, v8
	global_load_dword v93, v6, s[6:7]
	global_load_dword v94, v7, s[8:9]
	global_load_dword v95, v8, s[42:43]
	s_mov_b64 exec, -1
	s_mov_b64 exec, s[58:59]
	s_waitcnt vmcnt(30)
	v_fma_f32 v0, v62, v61, v60
	v_fma_f32 v1, v65, v64, v63
	v_mul_f32_e32 v2, 0xbfb8aa3b, v0
	v_exp_f32_e32 v2, v2
	s_nop 0
	v_add_f32_e32 v2, 1.0, v2
	v_rcp_f32_e32 v2, v2
	s_nop 0
	v_mul_f32_e32 v2, v0, v2
	v_mul_f32_e32 v2, v1, v2
	v_cvt_pk_bf16_f32 v2, v2, v2
	global_store_short v100, v2, s[82:83]
	s_mov_b64 exec, s[60:61]
	s_waitcnt vmcnt(25)
	v_fma_f32 v0, v68, v67, v66
	v_fma_f32 v1, v71, v70, v69
	v_mul_f32_e32 v2, 0xbfb8aa3b, v0
	v_exp_f32_e32 v2, v2
	s_nop 0
	v_add_f32_e32 v2, 1.0, v2
	v_rcp_f32_e32 v2, v2
	s_nop 0
	v_mul_f32_e32 v2, v0, v2
	v_mul_f32_e32 v2, v1, v2
	v_cvt_pk_bf16_f32 v2, v2, v2
	global_store_short v101, v2, s[82:83]
	s_mov_b64 exec, s[62:63]
	s_waitcnt vmcnt(20)
	v_fma_f32 v0, v74, v73, v72
	v_fma_f32 v1, v77, v76, v75
	v_mul_f32_e32 v2, 0xbfb8aa3b, v0
	v_exp_f32_e32 v2, v2
	s_nop 0
	v_add_f32_e32 v2, 1.0, v2
	v_rcp_f32_e32 v2, v2
	s_nop 0
	v_mul_f32_e32 v2, v0, v2
	v_mul_f32_e32 v2, v1, v2
	v_cvt_pk_bf16_f32 v2, v2, v2
	global_store_short v102, v2, s[82:83]
	s_mov_b64 exec, s[64:65]
	s_waitcnt vmcnt(15)
	v_fma_f32 v0, v80, v79, v78
	v_fma_f32 v1, v83, v82, v81
	v_mul_f32_e32 v2, 0xbfb8aa3b, v0
	v_exp_f32_e32 v2, v2
	s_nop 0
	v_add_f32_e32 v2, 1.0, v2
	v_rcp_f32_e32 v2, v2
	s_nop 0
	v_mul_f32_e32 v2, v0, v2
	v_mul_f32_e32 v2, v1, v2
	v_cvt_pk_bf16_f32 v2, v2, v2
	global_store_short v103, v2, s[82:83]
	s_mov_b64 exec, s[66:67]
	s_waitcnt vmcnt(10)
	v_fma_f32 v0, v86, v85, v84
	v_fma_f32 v1, v89, v88, v87
	v_mul_f32_e32 v2, 0xbfb8aa3b, v0
	v_exp_f32_e32 v2, v2
	s_nop 0
	v_add_f32_e32 v2, 1.0, v2
	v_rcp_f32_e32 v2, v2
	s_nop 0
	v_mul_f32_e32 v2, v0, v2
	v_mul_f32_e32 v2, v1, v2
	v_cvt_pk_bf16_f32 v2, v2, v2
	global_store_short v104, v2, s[82:83]
	s_mov_b64 exec, s[68:69]
	s_waitcnt vmcnt(5)
	v_fma_f32 v0, v92, v91, v90
	v_fma_f32 v1, v95, v94, v93
	v_mul_f32_e32 v2, 0xbfb8aa3b, v0
	v_exp_f32_e32 v2, v2
	s_nop 0
	v_add_f32_e32 v2, 1.0, v2
	v_rcp_f32_e32 v2, v2
	s_nop 0
	v_mul_f32_e32 v2, v0, v2
	v_mul_f32_e32 v2, v1, v2
	v_cvt_pk_bf16_f32 v2, v2, v2
	global_store_short v105, v2, s[82:83]
	s_mov_b64 exec, -1
	s_mov_b64 s[4:5], -1
	s_branch .LBB0_1588
.Lfx_generic:
	v_add_u32_e32 v2, s0, v243
	v_cmp_gt_i32_e32 vcc, s20, v2
	s_and_saveexec_b64 s[4:5], vcc
	s_cbranch_execz .LBB0_1588
	s_add_u32 s6, s76, 0x18b00000
	s_addc_u32 s7, s77, 0
	s_add_u32 s8, s76, 0x18c00000
	s_addc_u32 s9, s77, 0
	s_lshr_b32 s0, s96, 1
	s_and_b32 s21, s0, 14
	s_lshl_b32 s16, s92, 9
	s_and_b64 s[0:1], s[70:71], exec
	s_cselect_b32 s22, 0x200, s16
	s_mov_b64 s[16:17], 0
	s_mov_b32 s23, 0x2e8ba2e9
	v_mov_b32_e32 v1, 0
	s_mov_b32 s24, 0xb000
	s_movk_i32 s25, 0x5000
	s_movk_i32 s26, 0x2c00
	v_mov_b32_e32 v3, 0x16000
	v_mov_b32_e32 v4, 0xff
	s_branch .LBB0_1581
